# post phase: the item's six data and weight float4 loads issued together with the statistics load (one memory round trip per item instead of three)
# speedup vs baseline: 1.0278x; 1.0032x over previous
; __device__ __forceinline__ unsigned pack2(float a, float b) { return (unsigned)f2bf(a) | ((unsigned)f2bf(b) << 16); }
; __device__ __forceinline__ float bflo(unsigned u) { return __uint_as_float(u << 16); }
; __device__ __forceinline__ float bfhi(unsigned u) { return __uint_as_float(u & 0xffff0000u); }
; __device__ __forceinline__ void phase_post(const Params& p, int l) {
;     ...
;   for (int it = blockIdx.x; it < NT / 4; it += gridDim.x) {
;     const int row = it * 4 + wave;
;     float rs; const float* nw;
;     if (lane < 32) {
;       const int g = lane >> 4;
;       const float4 a = *(const float4*)(STAT + (size_t)row * 32 + g * 4);
;       const float s = (a.x + a.y) + (a.z + a.w);
;       rs = rsqrtf(s * (1.f / 256.f) + 1e-5f);
;       nw = snw + lane * 16;
;     } else {
;       const int hh = (lane - 32) >> 3;
;       const float4 a = *(const float4*)(STAT + (size_t)row * 32 + 16 + hh * 4);
;       const float s = (a.x + a.y) + (a.z + a.w);
;       rs = rsqrtf(s * (1.f / 128.f) + 1e-6f);
;       nw = gnw + ((lane - 32) & 7) * 16;
;     }
;     bf16_t* ptr = BR + (size_t)row * 1536 + 512 + lane * 16;
; #pragma unroll
;     for (int q = 0; q < 2; ++q) {
;       uint4 u = *(const uint4*)(ptr + q * 8);
;       const float4 w0 = *(const float4*)(nw + q * 8);
;       const float4 w1 = *(const float4*)(nw + q * 8 + 4);
;       u.x = pack2(bflo(u.x) * rs * w0.x, bfhi(u.x) * rs * w0.y);
;       u.y = pack2(bflo(u.y) * rs * w0.z, bfhi(u.y) * rs * w0.w);
;       u.z = pack2(bflo(u.z) * rs * w1.x, bfhi(u.z) * rs * w1.y);
;       u.w = pack2(bflo(u.w) * rs * w1.z, bfhi(u.w) * rs * w1.w);
;       *(uint4*)(ptr + q * 8) = u;
;     }
.LBB0_29:
	s_or_b64 exec, exec, s[14:15]
	global_load_dwordx4 v[4:7], v[4:5], off
	s_waitcnt vmcnt(7)
	v_mad_i64_i32 v[22:23], s[14:15], v20, s78, v[18:19]
	global_load_dwordx4 v[40:43], v[22:23], off offset:1040
	global_load_dwordx4 v[44:47], v[22:23], off offset:1024
	global_load_dwordx4 v[48:51], v[24:25], off offset:16
	global_load_dwordx4 v[52:55], v[24:25], off
	global_load_dwordx4 v[56:59], v[24:25], off offset:48
	global_load_dwordx4 v[60:63], v[24:25], off offset:32
	s_add_i32 s18, s18, s16
	v_add_u32_e32 v20, s17, v20
	s_cmpk_gt_i32 s18, 0x103f
	s_waitcnt vmcnt(0)
	v_mov_b32_e32 v10, v5
	v_mov_b32_e32 v11, v6
	v_mov_b32_e32 v5, v7
	v_pk_add_f32 v[4:5], v[10:11], v[4:5]
	s_nop 0
	v_add_f32_e32 v4, v4, v5
	v_fmac_f32_e32 v2, v8, v4
	v_cmp_gt_f32_e32 vcc, s72, v2
	v_mul_f32_e32 v4, 0x4b800000, v2
	s_nop 0
	v_cndmask_b32_e32 v2, v2, v4, vcc
	v_rsq_f32_e32 v2, v2
	s_nop 0
	v_mul_f32_e32 v4, 0x45800000, v2
	v_cndmask_b32_e32 v2, v2, v4, vcc
	v_mov_b32_e32 v4, v40
	v_mov_b32_e32 v5, v41
	v_mov_b32_e32 v6, v42
	v_mov_b32_e32 v7, v43
	v_mov_b32_e32 v26, v44
	v_mov_b32_e32 v27, v45
	v_mov_b32_e32 v28, v46
	v_mov_b32_e32 v29, v47
	v_mov_b32_e32 v8, v48
	v_mov_b32_e32 v9, v49
	v_mov_b32_e32 v10, v50
	v_mov_b32_e32 v11, v51
	v_mov_b32_e32 v30, v52
	v_mov_b32_e32 v31, v53
	v_mov_b32_e32 v32, v54
	v_mov_b32_e32 v33, v55
	s_waitcnt vmcnt(2)
	v_lshlrev_b32_e32 v35, 16, v27
	v_lshlrev_b32_e32 v34, 16, v26
	v_and_b32_e32 v27, 0xffff0000, v27
	v_and_b32_e32 v26, 0xffff0000, v26
	s_waitcnt vmcnt(0)
	v_mov_b32_e32 v37, v32
	v_pk_mul_f32 v[26:27], v[2:3], v[26:27] op_sel_hi:[0,1]
	v_mov_b32_e32 v32, v31
	v_pk_mul_f32 v[34:35], v[2:3], v[34:35] op_sel_hi:[0,1]
	v_mov_b32_e32 v36, v30
	v_pk_mul_f32 v[26:27], v[32:33], v[26:27]
	v_pk_mul_f32 v[34:35], v[36:37], v[34:35]
	v_and_b32_sdwa v32, v26, v183 dst_sel:DWORD dst_unused:UNUSED_PAD src0_sel:WORD_1 src1_sel:DWORD
	v_and_b32_sdwa v30, v34, v183 dst_sel:DWORD dst_unused:UNUSED_PAD src0_sel:WORD_1 src1_sel:DWORD
	v_add3_u32 v26, v26, v32, s37
	v_add3_u32 v30, v34, v30, s37
	v_and_b32_sdwa v31, v27, v183 dst_sel:DWORD dst_unused:UNUSED_PAD src0_sel:WORD_1 src1_sel:DWORD
	v_and_b32_e32 v26, 0xffff0000, v26
	v_add3_u32 v27, v27, v31, s37
	v_or_b32_sdwa v26, v26, v30 dst_sel:DWORD dst_unused:UNUSED_PAD src0_sel:DWORD src1_sel:WORD_1
	v_lshlrev_b32_e32 v31, 16, v29
	v_lshlrev_b32_e32 v30, 16, v28
	v_and_b32_e32 v29, 0xffff0000, v29
	v_and_b32_e32 v28, 0xffff0000, v28
	v_and_b32_sdwa v21, v35, v183 dst_sel:DWORD dst_unused:UNUSED_PAD src0_sel:WORD_1 src1_sel:DWORD
	v_mov_b32_e32 v33, v10
	v_pk_mul_f32 v[28:29], v[2:3], v[28:29] op_sel_hi:[0,1]
	v_mov_b32_e32 v10, v9
	v_add3_u32 v21, v35, v21, s37
	v_and_b32_e32 v27, 0xffff0000, v27
	v_pk_mul_f32 v[30:31], v[2:3], v[30:31] op_sel_hi:[0,1]
	v_mov_b32_e32 v32, v8
	v_pk_mul_f32 v[8:9], v[28:29], v[10:11]
	v_or_b32_sdwa v27, v27, v21 dst_sel:DWORD dst_unused:UNUSED_PAD src0_sel:DWORD src1_sel:WORD_1
	v_pk_mul_f32 v[30:31], v[32:33], v[30:31]
	v_and_b32_sdwa v21, v9, v183 dst_sel:DWORD dst_unused:UNUSED_PAD src0_sel:WORD_1 src1_sel:DWORD
	v_and_b32_sdwa v28, v8, v183 dst_sel:DWORD dst_unused:UNUSED_PAD src0_sel:WORD_1 src1_sel:DWORD
	v_and_b32_sdwa v10, v31, v183 dst_sel:DWORD dst_unused:UNUSED_PAD src0_sel:WORD_1 src1_sel:DWORD
	v_and_b32_sdwa v11, v30, v183 dst_sel:DWORD dst_unused:UNUSED_PAD src0_sel:WORD_1 src1_sel:DWORD
	v_add3_u32 v9, v9, v21, s37
	v_add3_u32 v8, v8, v28, s37
	v_add3_u32 v11, v30, v11, s37
	v_add3_u32 v10, v31, v10, s37
	v_and_b32_e32 v9, 0xffff0000, v9
	v_and_b32_e32 v8, 0xffff0000, v8
	v_or_b32_sdwa v29, v9, v10 dst_sel:DWORD dst_unused:UNUSED_PAD src0_sel:DWORD src1_sel:WORD_1
	v_or_b32_sdwa v28, v8, v11 dst_sel:DWORD dst_unused:UNUSED_PAD src0_sel:DWORD src1_sel:WORD_1
	global_store_dwordx4 v[22:23], v[26:29], off offset:1024
	v_mov_b32_e32 v8, v56
	v_mov_b32_e32 v9, v57
	v_mov_b32_e32 v10, v58
	v_mov_b32_e32 v11, v59
	s_nop 0
	v_mov_b32_e32 v24, v60
	v_mov_b32_e32 v25, v61
	v_mov_b32_e32 v26, v62
	v_mov_b32_e32 v27, v63
	v_lshlrev_b32_e32 v29, 16, v5
	v_lshlrev_b32_e32 v28, 16, v4
	v_and_b32_e32 v5, 0xffff0000, v5
	v_and_b32_e32 v4, 0xffff0000, v4
	v_pk_mul_f32 v[4:5], v[2:3], v[4:5] op_sel_hi:[0,1]
	v_pk_mul_f32 v[28:29], v[2:3], v[28:29] op_sel_hi:[0,1]
	v_mov_b32_e32 v31, v26
	v_mov_b32_e32 v26, v25
	v_mov_b32_e32 v30, v24
	v_pk_mul_f32 v[4:5], v[4:5], v[26:27]
	v_pk_mul_f32 v[28:29], v[28:29], v[30:31]
	v_and_b32_sdwa v26, v4, v183 dst_sel:DWORD dst_unused:UNUSED_PAD src0_sel:WORD_1 src1_sel:DWORD
	v_and_b32_sdwa v24, v28, v183 dst_sel:DWORD dst_unused:UNUSED_PAD src0_sel:WORD_1 src1_sel:DWORD
	v_add3_u32 v4, v4, v26, s37
	v_add3_u32 v24, v28, v24, s37
	v_and_b32_sdwa v25, v5, v183 dst_sel:DWORD dst_unused:UNUSED_PAD src0_sel:WORD_1 src1_sel:DWORD
	v_and_b32_e32 v4, 0xffff0000, v4
	v_add3_u32 v5, v5, v25, s37
	v_or_b32_sdwa v4, v4, v24 dst_sel:DWORD dst_unused:UNUSED_PAD src0_sel:DWORD src1_sel:WORD_1
	v_lshlrev_b32_e32 v25, 16, v7
	v_lshlrev_b32_e32 v24, 16, v6
	v_and_b32_e32 v7, 0xffff0000, v7
	v_and_b32_e32 v6, 0xffff0000, v6
	v_mov_b32_e32 v27, v10
	v_pk_mul_f32 v[6:7], v[2:3], v[6:7] op_sel_hi:[0,1]
	v_mov_b32_e32 v10, v9
	v_pk_mul_f32 v[24:25], v[2:3], v[24:25] op_sel_hi:[0,1]
	v_mov_b32_e32 v26, v8
	v_pk_mul_f32 v[6:7], v[6:7], v[10:11]
	v_pk_mul_f32 v[24:25], v[24:25], v[26:27]
	v_and_b32_sdwa v9, v7, v183 dst_sel:DWORD dst_unused:UNUSED_PAD src0_sel:WORD_1 src1_sel:DWORD
	v_and_b32_sdwa v10, v6, v183 dst_sel:DWORD dst_unused:UNUSED_PAD src0_sel:WORD_1 src1_sel:DWORD
	v_and_b32_sdwa v21, v29, v183 dst_sel:DWORD dst_unused:UNUSED_PAD src0_sel:WORD_1 src1_sel:DWORD
	v_and_b32_sdwa v2, v25, v183 dst_sel:DWORD dst_unused:UNUSED_PAD src0_sel:WORD_1 src1_sel:DWORD
	v_and_b32_sdwa v8, v24, v183 dst_sel:DWORD dst_unused:UNUSED_PAD src0_sel:WORD_1 src1_sel:DWORD
	v_add3_u32 v7, v7, v9, s37
	v_add3_u32 v6, v6, v10, s37
	v_add3_u32 v21, v29, v21, s37
	v_and_b32_e32 v5, 0xffff0000, v5
	v_add3_u32 v8, v24, v8, s37
	v_add3_u32 v2, v25, v2, s37
	v_and_b32_e32 v7, 0xffff0000, v7
	v_and_b32_e32 v6, 0xffff0000, v6
	v_or_b32_sdwa v5, v5, v21 dst_sel:DWORD dst_unused:UNUSED_PAD src0_sel:DWORD src1_sel:WORD_1
	v_or_b32_sdwa v7, v7, v2 dst_sel:DWORD dst_unused:UNUSED_PAD src0_sel:DWORD src1_sel:WORD_1
	v_or_b32_sdwa v6, v6, v8 dst_sel:DWORD dst_unused:UNUSED_PAD src0_sel:DWORD src1_sel:WORD_1
	global_store_dwordx4 v[22:23], v[4:7], off offset:1040
	s_cbranch_scc1 .LBB0_34
